# P5 out_proj: prefetch residual x tile into L2 during K-loop (1 global_load_dword per K iteration per wave), vmcnt(8)->(9) at two waits
# speedup vs baseline: 1.0118x; 1.0118x over previous
.LBB0_1263:
	s_ashr_i32 s23, s22, 31
	s_lshl_b64 s[24:25], s[22:23], 19
	s_add_u32 s24, s46, s24
	s_addc_u32 s25, s47, s25
	s_and_b64 s[26:27], s[0:1], exec
	s_cselect_b32 s23, s25, s35
	s_cselect_b32 s33, s24, s34
	s_ashr_i32 s21, s20, 31
	s_lshl_b64 s[26:27], s[20:21], 19
	s_add_u32 s26, s44, s26
	s_addc_u32 s27, s45, s27
	s_and_b64 s[38:39], s[0:1], exec
	s_cselect_b32 s21, s27, s37
	s_cselect_b32 s56, s26, s36
	s_add_u32 s34, s34, 0x40080
	s_addc_u32 s35, s35, 0
	s_add_u32 s57, s36, 0x100
	v_mov_b32_e32 v0, 0
	s_addc_u32 s58, s37, 0
	s_mov_b32 s59, -2
	s_lshl_b32 s98, s30, 20
	s_lshl_b32 s99, s28, 10
	s_add_u32 s98, s98, s99
	s_add_u32 s98, s40, s98
	s_addc_u32 s99, s41, 0
	v_bfe_u32 v255, v152, 3, 1
	v_and_b32_e32 v254, 0xffffffe0, v152
	v_lshl_add_u32 v254, v255, 7, v254
	v_lshlrev_b32_e32 v254, 2, v254
	v_lshl_add_u32 v254, v150, 12, v254
	v_mov_b32_e32 v1, v0
	v_mov_b32_e32 v2, v0
	v_mov_b32_e32 v3, v0
	v_mov_b32_e32 v4, v0
	v_mov_b32_e32 v5, v0
	v_mov_b32_e32 v6, v0
	v_mov_b32_e32 v7, v0
	v_mov_b32_e32 v8, v0
	v_mov_b32_e32 v9, v0
	v_mov_b32_e32 v10, v0
	v_mov_b32_e32 v11, v0
	v_mov_b32_e32 v12, v0
	v_mov_b32_e32 v13, v0
	v_mov_b32_e32 v14, v0
	v_mov_b32_e32 v15, v0
	v_mov_b32_e32 v20, v0
	v_mov_b32_e32 v21, v0
	v_mov_b32_e32 v22, v0
	v_mov_b32_e32 v23, v0
	v_mov_b32_e32 v24, v0
	v_mov_b32_e32 v25, v0
	v_mov_b32_e32 v26, v0
	v_mov_b32_e32 v27, v0
	v_mov_b32_e32 v32, v0
	v_mov_b32_e32 v33, v0
	v_mov_b32_e32 v34, v0
	v_mov_b32_e32 v35, v0
	v_mov_b32_e32 v40, v0
	v_mov_b32_e32 v41, v0
	v_mov_b32_e32 v42, v0
	v_mov_b32_e32 v43, v0
	v_mov_b32_e32 v16, v0
	v_mov_b32_e32 v17, v0
	v_mov_b32_e32 v18, v0
	v_mov_b32_e32 v19, v0
	v_mov_b32_e32 v28, v0
	v_mov_b32_e32 v29, v0
	v_mov_b32_e32 v30, v0
	v_mov_b32_e32 v31, v0
	v_mov_b32_e32 v36, v0
	v_mov_b32_e32 v37, v0
	v_mov_b32_e32 v38, v0
	v_mov_b32_e32 v39, v0
	v_mov_b32_e32 v44, v0
	v_mov_b32_e32 v45, v0
	v_mov_b32_e32 v46, v0
	v_mov_b32_e32 v47, v0
	v_mov_b32_e32 v48, v0
	v_mov_b32_e32 v49, v0
	v_mov_b32_e32 v50, v0
	v_mov_b32_e32 v51, v0
	v_mov_b32_e32 v52, v0
	v_mov_b32_e32 v53, v0
	v_mov_b32_e32 v54, v0
	v_mov_b32_e32 v55, v0
	v_mov_b32_e32 v56, v0
	v_mov_b32_e32 v57, v0
	v_mov_b32_e32 v58, v0
	v_mov_b32_e32 v59, v0
	v_mov_b32_e32 v60, v0
	v_mov_b32_e32 v61, v0
	v_mov_b32_e32 v62, v0
	v_mov_b32_e32 v63, v0
	v_mov_b32_e32 v64, v0
	v_mov_b32_e32 v65, v0
	v_mov_b32_e32 v66, v0
	v_mov_b32_e32 v67, v0
	v_mov_b32_e32 v68, v0
	v_mov_b32_e32 v69, v0
	v_mov_b32_e32 v70, v0
	v_mov_b32_e32 v71, v0
	v_mov_b32_e32 v72, v0
	v_mov_b32_e32 v73, v0
	v_mov_b32_e32 v74, v0
	v_mov_b32_e32 v75, v0
	v_mov_b32_e32 v76, v0
	v_mov_b32_e32 v77, v0
	v_mov_b32_e32 v78, v0
	v_mov_b32_e32 v79, v0
	v_mov_b32_e32 v84, v0
	v_mov_b32_e32 v85, v0
	v_mov_b32_e32 v86, v0
	v_mov_b32_e32 v87, v0
	v_mov_b32_e32 v88, v0
	v_mov_b32_e32 v89, v0
	v_mov_b32_e32 v90, v0
	v_mov_b32_e32 v91, v0
	v_mov_b32_e32 v96, v0
	v_mov_b32_e32 v97, v0
	v_mov_b32_e32 v98, v0
	v_mov_b32_e32 v99, v0
	v_mov_b32_e32 v104, v0
	v_mov_b32_e32 v105, v0
	v_mov_b32_e32 v106, v0
	v_mov_b32_e32 v107, v0
	v_mov_b32_e32 v80, v0
	v_mov_b32_e32 v81, v0
	v_mov_b32_e32 v82, v0
	v_mov_b32_e32 v83, v0
	v_mov_b32_e32 v92, v0
	v_mov_b32_e32 v93, v0
	v_mov_b32_e32 v94, v0
	v_mov_b32_e32 v95, v0
	v_mov_b32_e32 v100, v0
	v_mov_b32_e32 v101, v0
	v_mov_b32_e32 v102, v0
	v_mov_b32_e32 v103, v0
	v_mov_b32_e32 v108, v0
	v_mov_b32_e32 v109, v0
	v_mov_b32_e32 v110, v0
	v_mov_b32_e32 v111, v0
	v_mov_b32_e32 v112, v0
	v_mov_b32_e32 v113, v0
	v_mov_b32_e32 v114, v0
	v_mov_b32_e32 v115, v0
	v_mov_b32_e32 v116, v0
	v_mov_b32_e32 v117, v0
	v_mov_b32_e32 v118, v0
	v_mov_b32_e32 v119, v0
	v_mov_b32_e32 v120, v0
	v_mov_b32_e32 v121, v0
	v_mov_b32_e32 v122, v0
	v_mov_b32_e32 v123, v0
	v_mov_b32_e32 v124, v0
	v_mov_b32_e32 v125, v0
	v_mov_b32_e32 v126, v0
	v_mov_b32_e32 v127, v0
.LBB0_1264:
	ds_read_b128 v[144:147], v153
	ds_read_b128 v[156:159], v153 offset:1024
	ds_read_b128 v[160:163], v153 offset:2048
	ds_read_b128 v[164:167], v153 offset:3072
	ds_read_b128 v[168:171], v154
	ds_read_b128 v[172:175], v154 offset:1024
	ds_read_b128 v[176:179], v154 offset:2048
	ds_read_b128 v[180:183], v154 offset:3072
	s_add_u32 s36, s34, 0xfffc0080
	s_addc_u32 s37, s35, -1
	s_cmp_eq_u32 s59, 12
	s_cselect_b32 s39, s23, s37
	s_cselect_b32 s38, s33, s36
	s_cselect_b32 s37, s21, s58
	s_cselect_b32 s36, s56, s57
	v_lshl_add_u64 v[148:149], s[34:35], 0, v[136:137]
	s_add_i32 m0, s29, 0xc000
	ds_read_b128 v[184:187], v155
	ds_read_b128 v[188:191], v155 offset:1024
	ds_read_b128 v[192:195], v155 offset:2048
	ds_read_b128 v[196:199], v155 offset:3072
	ds_read_b128 v[200:203], v155 offset:4096
	ds_read_b128 v[204:207], v155 offset:5120
	ds_read_b128 v[208:211], v155 offset:6144
	ds_read_b128 v[212:215], v155 offset:7168
	global_load_lds_dwordx4 v[148:149], off
	v_lshl_add_u64 v[148:149], s[34:35], 0, v[138:139]
	s_add_i32 m0, s29, 0xe000
	s_nop 0
	global_load_lds_dwordx4 v[148:149], off
	s_waitcnt vmcnt(8)
	s_waitcnt lgkmcnt(0)
	s_barrier
	s_setprio 1
	s_waitcnt lgkmcnt(0)
	global_load_dword v253, v254, s[98:99]
	s_mov_b32 s100, 0x10000
	s_cmp_eq_u32 s59, 4
	s_cselect_b32 s100, 0x50000, s100
	s_add_u32 s98, s98, s100
	s_addc_u32 s99, s99, 0
	v_mfma_f32_16x16x32_bf16 v[124:127], v[144:147], v[184:187], v[124:127]
	v_mfma_f32_16x16x32_bf16 v[120:123], v[160:163], v[184:187], v[120:123]
	v_mfma_f32_16x16x32_bf16 v[116:119], v[144:147], v[192:195], v[116:119]
	v_mfma_f32_16x16x32_bf16 v[112:115], v[160:163], v[192:195], v[112:115]
	v_mfma_f32_16x16x32_bf16 v[108:111], v[144:147], v[200:203], v[108:111]
	v_mfma_f32_16x16x32_bf16 v[100:103], v[160:163], v[200:203], v[100:103]
	v_mfma_f32_16x16x32_bf16 v[92:95], v[144:147], v[208:211], v[92:95]
	v_mfma_f32_16x16x32_bf16 v[80:83], v[160:163], v[208:211], v[80:83]
	v_mfma_f32_16x16x32_bf16 v[124:127], v[156:159], v[188:191], v[124:127]
	v_mfma_f32_16x16x32_bf16 v[120:123], v[164:167], v[188:191], v[120:123]
	v_mfma_f32_16x16x32_bf16 v[116:119], v[156:159], v[196:199], v[116:119]
	v_mfma_f32_16x16x32_bf16 v[112:115], v[164:167], v[196:199], v[112:115]
	v_mfma_f32_16x16x32_bf16 v[108:111], v[156:159], v[204:207], v[108:111]
	v_mfma_f32_16x16x32_bf16 v[100:103], v[164:167], v[204:207], v[100:103]
	v_mfma_f32_16x16x32_bf16 v[92:95], v[156:159], v[212:215], v[92:95]
	v_mfma_f32_16x16x32_bf16 v[80:83], v[164:167], v[212:215], v[80:83]
	s_setprio 0
	s_setprio 1
	v_mfma_f32_16x16x32_bf16 v[104:107], v[168:171], v[184:187], v[104:107]
	v_mfma_f32_16x16x32_bf16 v[96:99], v[176:179], v[184:187], v[96:99]
	v_mfma_f32_16x16x32_bf16 v[88:91], v[168:171], v[192:195], v[88:91]
	v_mfma_f32_16x16x32_bf16 v[84:87], v[176:179], v[192:195], v[84:87]
	v_mfma_f32_16x16x32_bf16 v[76:79], v[168:171], v[200:203], v[76:79]
	v_mfma_f32_16x16x32_bf16 v[72:75], v[176:179], v[200:203], v[72:75]
	v_mfma_f32_16x16x32_bf16 v[68:71], v[168:171], v[208:211], v[68:71]
	v_mfma_f32_16x16x32_bf16 v[64:67], v[176:179], v[208:211], v[64:67]
	v_mfma_f32_16x16x32_bf16 v[104:107], v[172:175], v[188:191], v[104:107]
	v_mfma_f32_16x16x32_bf16 v[96:99], v[180:183], v[188:191], v[96:99]
	v_mfma_f32_16x16x32_bf16 v[88:91], v[172:175], v[196:199], v[88:91]
	v_mfma_f32_16x16x32_bf16 v[84:87], v[180:183], v[196:199], v[84:87]
	v_mfma_f32_16x16x32_bf16 v[76:79], v[172:175], v[204:207], v[76:79]
	v_mfma_f32_16x16x32_bf16 v[72:75], v[180:183], v[204:207], v[72:75]
	v_mfma_f32_16x16x32_bf16 v[68:71], v[172:175], v[212:215], v[68:71]
	v_mfma_f32_16x16x32_bf16 v[64:67], v[180:183], v[212:215], v[64:67]
	s_setprio 0
	s_barrier
	s_add_i32 s60, s54, s2
	v_lshl_add_u64 v[148:149], s[36:37], 0, v[130:131]
	s_mov_b32 m0, s60
	ds_read_b128 v[184:187], v155 offset:16384
	ds_read_b128 v[188:191], v155 offset:17408
	ds_read_b128 v[192:195], v155 offset:18432
	ds_read_b128 v[196:199], v155 offset:19456
	ds_read_b128 v[200:203], v155 offset:20480
	ds_read_b128 v[204:207], v155 offset:21504
	ds_read_b128 v[208:211], v155 offset:22528
	ds_read_b128 v[212:215], v155 offset:23552
	global_load_lds_dwordx4 v[148:149], off
	s_add_i32 m0, s60, 0x2000
	s_add_u32 s60, s36, 0x40000
	v_lshl_add_u64 v[216:217], s[36:37], 0, v[134:135]
	s_addc_u32 s61, s37, 0
	s_add_i32 s62, s55, s2
	global_load_lds_dwordx4 v[216:217], off
	v_lshl_add_u64 v[218:219], s[60:61], 0, v[130:131]
	s_mov_b32 m0, s62
	v_lshl_add_u64 v[220:221], s[38:39], 0, v[132:133]
	global_load_lds_dwordx4 v[218:219], off
	v_lshl_add_u64 v[218:219], s[60:61], 0, v[134:135]
	s_add_i32 m0, s62, 0x2000
	s_nop 0
	global_load_lds_dwordx4 v[218:219], off
	v_lshl_add_u64 v[218:219], s[38:39], 0, v[128:129]
	s_mov_b32 m0, s29
	s_nop 0
	global_load_lds_dwordx4 v[218:219], off
	s_mov_b32 m0, s31
	s_nop 0
	global_load_lds_dwordx4 v[220:221], off
	s_waitcnt vmcnt(9)
	s_waitcnt lgkmcnt(0)
	s_barrier
	s_setprio 1
	s_waitcnt lgkmcnt(0)
	v_mfma_f32_16x16x32_bf16 v[60:63], v[144:147], v[184:187], v[60:63]
	v_mfma_f32_16x16x32_bf16 v[56:59], v[160:163], v[184:187], v[56:59]
	v_mfma_f32_16x16x32_bf16 v[52:55], v[144:147], v[192:195], v[52:55]
	v_mfma_f32_16x16x32_bf16 v[48:51], v[160:163], v[192:195], v[48:51]
	v_mfma_f32_16x16x32_bf16 v[44:47], v[144:147], v[200:203], v[44:47]
	v_mfma_f32_16x16x32_bf16 v[36:39], v[160:163], v[200:203], v[36:39]
	v_mfma_f32_16x16x32_bf16 v[28:31], v[144:147], v[208:211], v[28:31]
	v_mfma_f32_16x16x32_bf16 v[16:19], v[160:163], v[208:211], v[16:19]
	v_mfma_f32_16x16x32_bf16 v[60:63], v[156:159], v[188:191], v[60:63]
	v_mfma_f32_16x16x32_bf16 v[56:59], v[164:167], v[188:191], v[56:59]
	v_mfma_f32_16x16x32_bf16 v[52:55], v[156:159], v[196:199], v[52:55]
	v_mfma_f32_16x16x32_bf16 v[48:51], v[164:167], v[196:199], v[48:51]
	v_mfma_f32_16x16x32_bf16 v[44:47], v[156:159], v[204:207], v[44:47]
	v_mfma_f32_16x16x32_bf16 v[36:39], v[164:167], v[204:207], v[36:39]
	v_mfma_f32_16x16x32_bf16 v[28:31], v[156:159], v[212:215], v[28:31]
	v_mfma_f32_16x16x32_bf16 v[16:19], v[164:167], v[212:215], v[16:19]
	s_setprio 0
	s_setprio 1
	v_mfma_f32_16x16x32_bf16 v[40:43], v[168:171], v[184:187], v[40:43]
	v_mfma_f32_16x16x32_bf16 v[32:35], v[176:179], v[184:187], v[32:35]
	v_mfma_f32_16x16x32_bf16 v[24:27], v[168:171], v[192:195], v[24:27]
	v_mfma_f32_16x16x32_bf16 v[20:23], v[176:179], v[192:195], v[20:23]
	v_mfma_f32_16x16x32_bf16 v[12:15], v[168:171], v[200:203], v[12:15]
	v_mfma_f32_16x16x32_bf16 v[8:11], v[176:179], v[200:203], v[8:11]
	v_mfma_f32_16x16x32_bf16 v[4:7], v[168:171], v[208:211], v[4:7]
	v_mfma_f32_16x16x32_bf16 v[0:3], v[176:179], v[208:211], v[0:3]
	v_mfma_f32_16x16x32_bf16 v[40:43], v[172:175], v[188:191], v[40:43]
	v_mfma_f32_16x16x32_bf16 v[32:35], v[180:183], v[188:191], v[32:35]
	v_mfma_f32_16x16x32_bf16 v[24:27], v[172:175], v[196:199], v[24:27]
	v_mfma_f32_16x16x32_bf16 v[20:23], v[180:183], v[196:199], v[20:23]
	v_mfma_f32_16x16x32_bf16 v[12:15], v[172:175], v[204:207], v[12:15]
	v_mfma_f32_16x16x32_bf16 v[8:11], v[180:183], v[204:207], v[8:11]
	v_mfma_f32_16x16x32_bf16 v[4:7], v[172:175], v[212:215], v[4:7]
	v_mfma_f32_16x16x32_bf16 v[0:3], v[180:183], v[212:215], v[0:3]
	s_setprio 0
	s_barrier
	s_add_i32 s60, 0, 0x18000
	v_add_u32_e32 v164, s60, v151
	v_add_u32_e32 v180, s92, v151
	ds_read_b128 v[144:147], v164
	ds_read_b128 v[156:159], v164 offset:1024
	ds_read_b128 v[160:163], v164 offset:2048
	ds_read_b128 v[164:167], v164 offset:3072
	ds_read_b128 v[168:171], v180
	ds_read_b128 v[172:175], v180 offset:1024
	ds_read_b128 v[176:179], v180 offset:2048
	ds_read_b128 v[180:183], v180 offset:3072
	s_add_u32 s38, s38, 0x40000
	s_addc_u32 s39, s39, 0
	s_mov_b32 m0, s48
	v_lshl_add_u64 v[222:223], s[38:39], 0, v[128:129]
	ds_read_b128 v[184:187], v155 offset:32768
	ds_read_b128 v[188:191], v155 offset:33792
	ds_read_b128 v[192:195], v155 offset:34816
	ds_read_b128 v[196:199], v155 offset:35840
	ds_read_b128 v[200:203], v155 offset:36864
	ds_read_b128 v[204:207], v155 offset:37888
	ds_read_b128 v[208:211], v155 offset:38912
	ds_read_b128 v[212:215], v155 offset:39936
	global_load_lds_dwordx4 v[222:223], off
	v_lshl_add_u64 v[222:223], s[38:39], 0, v[132:133]
	s_mov_b32 m0, s49
	s_nop 0
	global_load_lds_dwordx4 v[222:223], off
	s_waitcnt vmcnt(9)
	s_waitcnt lgkmcnt(0)
	s_barrier
	s_setprio 1
	s_waitcnt lgkmcnt(0)
	v_mfma_f32_16x16x32_bf16 v[124:127], v[144:147], v[184:187], v[124:127]
	v_mfma_f32_16x16x32_bf16 v[120:123], v[160:163], v[184:187], v[120:123]
	v_mfma_f32_16x16x32_bf16 v[116:119], v[144:147], v[192:195], v[116:119]
	v_mfma_f32_16x16x32_bf16 v[112:115], v[160:163], v[192:195], v[112:115]
	v_mfma_f32_16x16x32_bf16 v[108:111], v[144:147], v[200:203], v[108:111]
	v_mfma_f32_16x16x32_bf16 v[100:103], v[160:163], v[200:203], v[100:103]
	v_mfma_f32_16x16x32_bf16 v[92:95], v[144:147], v[208:211], v[92:95]
	v_mfma_f32_16x16x32_bf16 v[80:83], v[160:163], v[208:211], v[80:83]
	v_mfma_f32_16x16x32_bf16 v[124:127], v[156:159], v[188:191], v[124:127]
	v_mfma_f32_16x16x32_bf16 v[120:123], v[164:167], v[188:191], v[120:123]
	v_mfma_f32_16x16x32_bf16 v[116:119], v[156:159], v[196:199], v[116:119]
	v_mfma_f32_16x16x32_bf16 v[112:115], v[164:167], v[196:199], v[112:115]
	v_mfma_f32_16x16x32_bf16 v[108:111], v[156:159], v[204:207], v[108:111]
	v_mfma_f32_16x16x32_bf16 v[100:103], v[164:167], v[204:207], v[100:103]
	v_mfma_f32_16x16x32_bf16 v[92:95], v[156:159], v[212:215], v[92:95]
	v_mfma_f32_16x16x32_bf16 v[80:83], v[164:167], v[212:215], v[80:83]
	s_setprio 0
	s_setprio 1
	v_mfma_f32_16x16x32_bf16 v[104:107], v[168:171], v[184:187], v[104:107]
	v_mfma_f32_16x16x32_bf16 v[96:99], v[176:179], v[184:187], v[96:99]
	v_mfma_f32_16x16x32_bf16 v[88:91], v[168:171], v[192:195], v[88:91]
	v_mfma_f32_16x16x32_bf16 v[84:87], v[176:179], v[192:195], v[84:87]
	v_mfma_f32_16x16x32_bf16 v[76:79], v[168:171], v[200:203], v[76:79]
	v_mfma_f32_16x16x32_bf16 v[72:75], v[176:179], v[200:203], v[72:75]
	v_mfma_f32_16x16x32_bf16 v[68:71], v[168:171], v[208:211], v[68:71]
	v_mfma_f32_16x16x32_bf16 v[64:67], v[176:179], v[208:211], v[64:67]
	v_mfma_f32_16x16x32_bf16 v[104:107], v[172:175], v[188:191], v[104:107]
	v_mfma_f32_16x16x32_bf16 v[96:99], v[180:183], v[188:191], v[96:99]
	v_mfma_f32_16x16x32_bf16 v[88:91], v[172:175], v[196:199], v[88:91]
	v_mfma_f32_16x16x32_bf16 v[84:87], v[180:183], v[196:199], v[84:87]
	v_mfma_f32_16x16x32_bf16 v[76:79], v[172:175], v[204:207], v[76:79]
	v_mfma_f32_16x16x32_bf16 v[72:75], v[180:183], v[204:207], v[72:75]
	v_mfma_f32_16x16x32_bf16 v[68:71], v[172:175], v[212:215], v[68:71]
	v_mfma_f32_16x16x32_bf16 v[64:67], v[180:183], v[212:215], v[64:67]
	s_setprio 0
	s_barrier
	s_add_i32 s38, s60, s2
	v_lshl_add_u64 v[148:149], v[148:149], 0, s[6:7]
	s_mov_b32 m0, s38
	ds_read_b128 v[184:187], v155 offset:49152
	ds_read_b128 v[188:191], v155 offset:50176
	ds_read_b128 v[192:195], v155 offset:51200
	ds_read_b128 v[196:199], v155 offset:52224
	ds_read_b128 v[200:203], v155 offset:53248
	ds_read_b128 v[204:207], v155 offset:54272
	ds_read_b128 v[208:211], v155 offset:55296
	ds_read_b128 v[212:215], v155 offset:56320
	global_load_lds_dwordx4 v[148:149], off
	s_add_i32 m0, s38, 0x2000
	s_add_u32 s36, s36, 0x40080
	v_lshl_add_u64 v[148:149], v[216:217], 0, s[6:7]
	s_addc_u32 s37, s37, 0
	s_add_i32 s38, s92, s2
	global_load_lds_dwordx4 v[148:149], off
	v_lshl_add_u64 v[148:149], s[36:37], 0, v[130:131]
	s_mov_b32 m0, s38
	s_nop 0
	global_load_lds_dwordx4 v[148:149], off
	v_lshl_add_u64 v[148:149], s[36:37], 0, v[134:135]
	s_add_i32 m0, s38, 0x2000
	s_nop 0
	global_load_lds_dwordx4 v[148:149], off
	v_lshl_add_u64 v[148:149], v[218:219], 0, s[6:7]
	s_mov_b32 m0, s51
	s_nop 0
	global_load_lds_dwordx4 v[148:149], off
	v_lshl_add_u64 v[148:149], v[220:221], 0, s[6:7]
	s_mov_b32 m0, s52
	s_nop 0
	global_load_lds_dwordx4 v[148:149], off
	s_waitcnt vmcnt(8)
	s_waitcnt lgkmcnt(0)
	s_barrier
	s_setprio 1
	s_waitcnt lgkmcnt(0)
	v_mfma_f32_16x16x32_bf16 v[60:63], v[144:147], v[184:187], v[60:63]
	v_mfma_f32_16x16x32_bf16 v[56:59], v[160:163], v[184:187], v[56:59]
	v_mfma_f32_16x16x32_bf16 v[52:55], v[144:147], v[192:195], v[52:55]
	v_mfma_f32_16x16x32_bf16 v[48:51], v[160:163], v[192:195], v[48:51]
	v_mfma_f32_16x16x32_bf16 v[44:47], v[144:147], v[200:203], v[44:47]
	v_mfma_f32_16x16x32_bf16 v[36:39], v[160:163], v[200:203], v[36:39]
	v_mfma_f32_16x16x32_bf16 v[28:31], v[144:147], v[208:211], v[28:31]
	v_mfma_f32_16x16x32_bf16 v[16:19], v[160:163], v[208:211], v[16:19]
	v_mfma_f32_16x16x32_bf16 v[60:63], v[156:159], v[188:191], v[60:63]
	v_mfma_f32_16x16x32_bf16 v[56:59], v[164:167], v[188:191], v[56:59]
	v_mfma_f32_16x16x32_bf16 v[52:55], v[156:159], v[196:199], v[52:55]
	v_mfma_f32_16x16x32_bf16 v[48:51], v[164:167], v[196:199], v[48:51]
	v_mfma_f32_16x16x32_bf16 v[44:47], v[156:159], v[204:207], v[44:47]
	v_mfma_f32_16x16x32_bf16 v[36:39], v[164:167], v[204:207], v[36:39]
	v_mfma_f32_16x16x32_bf16 v[28:31], v[156:159], v[212:215], v[28:31]
	v_mfma_f32_16x16x32_bf16 v[16:19], v[164:167], v[212:215], v[16:19]
	s_setprio 0
	s_setprio 1
	v_mfma_f32_16x16x32_bf16 v[40:43], v[168:171], v[184:187], v[40:43]
	v_mfma_f32_16x16x32_bf16 v[32:35], v[176:179], v[184:187], v[32:35]
	v_mfma_f32_16x16x32_bf16 v[24:27], v[168:171], v[192:195], v[24:27]
	v_mfma_f32_16x16x32_bf16 v[20:23], v[176:179], v[192:195], v[20:23]
	v_mfma_f32_16x16x32_bf16 v[12:15], v[168:171], v[200:203], v[12:15]
	v_mfma_f32_16x16x32_bf16 v[8:11], v[176:179], v[200:203], v[8:11]
	v_mfma_f32_16x16x32_bf16 v[4:7], v[168:171], v[208:211], v[4:7]
	v_mfma_f32_16x16x32_bf16 v[0:3], v[176:179], v[208:211], v[0:3]
	v_mfma_f32_16x16x32_bf16 v[40:43], v[172:175], v[188:191], v[40:43]
	v_mfma_f32_16x16x32_bf16 v[32:35], v[180:183], v[188:191], v[32:35]
	v_mfma_f32_16x16x32_bf16 v[24:27], v[172:175], v[196:199], v[24:27]
	v_mfma_f32_16x16x32_bf16 v[20:23], v[180:183], v[196:199], v[20:23]
	v_mfma_f32_16x16x32_bf16 v[12:15], v[172:175], v[204:207], v[12:15]
	v_mfma_f32_16x16x32_bf16 v[8:11], v[180:183], v[204:207], v[8:11]
	v_mfma_f32_16x16x32_bf16 v[4:7], v[172:175], v[212:215], v[4:7]
	v_mfma_f32_16x16x32_bf16 v[0:3], v[180:183], v[212:215], v[0:3]
	s_setprio 0
	s_barrier
	s_add_i32 s59, s59, 2
	s_add_u32 s34, s34, 0x100
	s_addc_u32 s35, s35, 0
	s_add_u32 s57, s57, 0x100
	s_addc_u32 s58, s58, 0
	s_cmp_gt_u32 s59, 13
	s_cbranch_scc0 .LBB0_1264
	s_and_b64 vcc, exec, s[8:9]
	s_cbranch_vccz .LBB0_1268
	s_barrier
	s_andn2_b64 vcc, exec, s[10:11]
	s_cbranch_vccz .LBB0_1269

	.amdhsa_kernel _Z9hymba_fwd4Args
		.amdhsa_group_segment_fixed_size 0
		.amdhsa_private_segment_fixed_size 0
		.amdhsa_kernarg_size 504
		.amdhsa_user_sgpr_count 2
		.amdhsa_user_sgpr_dispatch_ptr 0
		.amdhsa_user_sgpr_queue_ptr 0
		.amdhsa_user_sgpr_kernarg_segment_ptr 1
		.amdhsa_user_sgpr_dispatch_id 0
		.amdhsa_user_sgpr_kernarg_preload_length 0
		.amdhsa_user_sgpr_kernarg_preload_offset 0
		.amdhsa_user_sgpr_private_segment_size 0
		.amdhsa_uses_dynamic_stack 0
		.amdhsa_enable_private_segment 0
		.amdhsa_system_sgpr_workgroup_id_x 1
		.amdhsa_system_sgpr_workgroup_id_y 0
		.amdhsa_system_sgpr_workgroup_id_z 0
		.amdhsa_system_sgpr_workgroup_info 0
		.amdhsa_system_vgpr_workitem_id 0
		.amdhsa_next_free_vgpr 256
		.amdhsa_next_free_sgpr 102
		.amdhsa_accum_offset 256
		.amdhsa_reserve_vcc 1
		.amdhsa_float_round_mode_32 0
		.amdhsa_float_round_mode_16_64 0
		.amdhsa_float_denorm_mode_32 3
		.amdhsa_float_denorm_mode_16_64 3
		.amdhsa_dx10_clamp 1
		.amdhsa_ieee_mode 1
		.amdhsa_fp16_overflow 0
		.amdhsa_tg_split 0
		.amdhsa_exception_fp_ieee_invalid_op 0
		.amdhsa_exception_fp_denorm_src 0
		.amdhsa_exception_fp_ieee_div_zero 0
		.amdhsa_exception_fp_ieee_overflow 0
		.amdhsa_exception_fp_ieee_underflow 0
		.amdhsa_exception_fp_ieee_inexact 0
		.amdhsa_exception_int_div_zero 0
	.end_amdhsa_kernel

amdhsa.kernels:
  - .agpr_count:     0
    .args:
      - .offset:         0
        .size:           248
        .value_kind:     by_value
      - .offset:         248
        .size:           4
        .value_kind:     hidden_block_count_x
      - .offset:         252
        .size:           4
        .value_kind:     hidden_block_count_y
      - .offset:         256
        .size:           4
        .value_kind:     hidden_block_count_z
      - .offset:         260
        .size:           2
        .value_kind:     hidden_group_size_x
      - .offset:         262
        .size:           2
        .value_kind:     hidden_group_size_y
      - .offset:         264
        .size:           2
        .value_kind:     hidden_group_size_z
      - .offset:         266
        .size:           2
        .value_kind:     hidden_remainder_x
      - .offset:         268
        .size:           2
        .value_kind:     hidden_remainder_y
      - .offset:         270
        .size:           2
        .value_kind:     hidden_remainder_z
      - .offset:         288
        .size:           8
        .value_kind:     hidden_global_offset_x
      - .offset:         296
        .size:           8
        .value_kind:     hidden_global_offset_y
      - .offset:         304
        .size:           8
        .value_kind:     hidden_global_offset_z
      - .offset:         312
        .size:           2
        .value_kind:     hidden_grid_dims
      - .offset:         368
        .size:           4
        .value_kind:     hidden_dynamic_lds_size
    .group_segment_fixed_size: 0
    .kernarg_segment_align: 8
    .kernarg_segment_size: 504
    .language:       OpenCL C
    .language_version:
      - 2
      - 0
    .max_flat_workgroup_size: 512
    .name:           _Z9hymba_fwd4Args
    .private_segment_fixed_size: 0
    .sgpr_count:     108
    .sgpr_spill_count: 82
    .symbol:         _Z9hymba_fwd4Args.kd
    .uniform_work_group_size: 1
    .uses_dynamic_stack: false
    .vgpr_count:     256
    .vgpr_spill_count: 0
    .wavefront_size: 64
